# hand-written out-proj epilogue: x loads batched ahead of Z stores (two halves), same f32 math
# baseline (speedup 1.0000x reference)
; #define GCOMPUTE(AS, BS) GCOMPUTE_KS(AS, BS, 0) GCOMPUTE_KS(AS, BS, 1)
; template <int EPI>
; DI void gemm_phase(const P& p, int l, const u16* __restrict__ A, const u16* __restrict__ Bt, int mpx, char* lds) {
;     ...
;   __syncthreads();
;   __builtin_amdgcn_sched_barrier(0);
;   GCOMPUTE(As1, Bs1)
;   __builtin_amdgcn_sched_barrier(0);
.Lgemm_out_exit:
	v_mfma_f32_16x16x32_bf16 v[134:137], v[246:249], v[162:165], v[134:137]
	v_mfma_f32_16x16x32_bf16 v[138:141], v[246:249], v[166:169], v[138:141]
	v_mfma_f32_16x16x32_bf16 v[142:145], v[246:249], v[170:173], v[142:145]
	v_mfma_f32_16x16x32_bf16 v[146:149], v[246:249], v[174:177], v[146:149]
	v_mfma_f32_16x16x32_bf16 v[150:153], v[250:253], v[162:165], v[150:153]
	v_mfma_f32_16x16x32_bf16 v[154:157], v[250:253], v[166:169], v[154:157]
	v_mfma_f32_16x16x32_bf16 v[158:161], v[250:253], v[170:173], v[158:161]
	v_mfma_f32_16x16x32_bf16 v[2:5], v[250:253], v[174:177], v[2:5]
	s_barrier
	ds_read_b128 v[162:165], v231
	ds_read_b128 v[166:169], v230
	ds_read_b128 v[170:173], v230 offset:2048
	ds_read_b128 v[174:177], v230 offset:4096
	ds_read_b128 v[178:181], v230 offset:6144
	s_waitcnt lgkmcnt(3)
	v_mfma_f32_16x16x32_bf16 v[6:9], v[162:165], v[166:169], v[6:9]
	s_waitcnt lgkmcnt(2)
	v_mfma_f32_16x16x32_bf16 v[10:13], v[162:165], v[170:173], v[10:13]
	s_waitcnt lgkmcnt(1)
	v_mfma_f32_16x16x32_bf16 v[14:17], v[162:165], v[174:177], v[14:17]
	s_waitcnt lgkmcnt(0)
	v_mfma_f32_16x16x32_bf16 v[22:25], v[162:165], v[178:181], v[22:25]
	ds_read_b128 v[162:165], v231 offset:2048
	s_waitcnt lgkmcnt(0)
	v_mfma_f32_16x16x32_bf16 v[26:29], v[162:165], v[166:169], v[26:29]
	v_mfma_f32_16x16x32_bf16 v[30:33], v[162:165], v[170:173], v[30:33]
	v_mfma_f32_16x16x32_bf16 v[34:37], v[162:165], v[174:177], v[34:37]
	v_mfma_f32_16x16x32_bf16 v[38:41], v[162:165], v[178:181], v[38:41]
	ds_read_b128 v[162:165], v231 offset:4096
	s_waitcnt lgkmcnt(0)
	v_mfma_f32_16x16x32_bf16 v[42:45], v[162:165], v[166:169], v[42:45]
	v_mfma_f32_16x16x32_bf16 v[46:49], v[162:165], v[170:173], v[46:49]
	v_mfma_f32_16x16x32_bf16 v[50:53], v[162:165], v[174:177], v[50:53]
	v_mfma_f32_16x16x32_bf16 v[54:57], v[162:165], v[178:181], v[54:57]
	ds_read_b128 v[162:165], v231 offset:6144
	s_waitcnt lgkmcnt(0)
	v_mfma_f32_16x16x32_bf16 v[58:61], v[162:165], v[166:169], v[58:61]
	v_mfma_f32_16x16x32_bf16 v[62:65], v[162:165], v[170:173], v[62:65]
	v_mfma_f32_16x16x32_bf16 v[66:69], v[162:165], v[174:177], v[66:69]
	v_mfma_f32_16x16x32_bf16 v[162:165], v[162:165], v[178:181], v[70:73]
	s_nop 2
	ds_read_b128 v[70:73], v231 offset:8192
	s_waitcnt lgkmcnt(0)
	v_mfma_f32_16x16x32_bf16 v[182:185], v[70:73], v[166:169], v[74:77]
	s_nop 2
	ds_read_b128 v[74:77], v233
	v_mfma_f32_16x16x32_bf16 v[186:189], v[70:73], v[170:173], v[78:81]
	v_mfma_f32_16x16x32_bf16 v[190:193], v[70:73], v[174:177], v[82:85]
	v_mfma_f32_16x16x32_bf16 v[212:215], v[70:73], v[178:181], v[114:117]
	ds_read_b128 v[70:73], v231 offset:10240
	s_waitcnt lgkmcnt(0)
	v_mfma_f32_16x16x32_bf16 v[216:219], v[70:73], v[166:169], v[118:121]
	v_mfma_f32_16x16x32_bf16 v[220:223], v[70:73], v[170:173], v[122:125]
	v_mfma_f32_16x16x32_bf16 v[234:237], v[70:73], v[174:177], v[126:129]
	v_mfma_f32_16x16x32_bf16 v[238:241], v[70:73], v[178:181], v[130:133]
	ds_read_b128 v[70:73], v231 offset:12288
	s_waitcnt lgkmcnt(0)
	v_mfma_f32_16x16x32_bf16 v[242:245], v[70:73], v[166:169], v[134:137]
	v_mfma_f32_16x16x32_bf16 v[246:249], v[70:73], v[170:173], v[138:141]
	v_mfma_f32_16x16x32_bf16 v[250:253], v[70:73], v[174:177], v[142:145]
	v_mfma_f32_16x16x32_bf16 v[208:211], v[70:73], v[178:181], v[146:149]
	ds_read_b128 v[70:73], v231 offset:14336
	s_waitcnt lgkmcnt(0)
	v_mfma_f32_16x16x32_bf16 v[178:181], v[70:73], v[178:181], v[2:5]
	s_nop 2
	ds_read_b128 v[2:5], v232
	s_waitcnt lgkmcnt(0)
	v_mfma_f32_16x16x32_bf16 v[146:149], v[74:77], v[2:5], v[6:9]
	s_nop 2
	ds_read_b128 v[6:9], v232 offset:2048
	v_mfma_f32_16x16x32_bf16 v[170:173], v[70:73], v[170:173], v[154:157]
	s_waitcnt lgkmcnt(0)
	v_mfma_f32_16x16x32_bf16 v[154:157], v[74:77], v[6:9], v[10:13]
	s_nop 2
	ds_read_b128 v[10:13], v232 offset:4096
	v_mfma_f32_16x16x32_bf16 v[166:169], v[70:73], v[166:169], v[150:153]
	s_waitcnt lgkmcnt(0)
	v_mfma_f32_16x16x32_bf16 v[150:153], v[74:77], v[10:13], v[14:17]
	s_nop 2
	ds_read_b128 v[14:17], v232 offset:6144
	v_mfma_f32_16x16x32_bf16 v[174:177], v[70:73], v[174:177], v[158:161]
	s_waitcnt lgkmcnt(0)
	v_mfma_f32_16x16x32_bf16 v[158:161], v[74:77], v[14:17], v[22:25]
	s_nop 2
	ds_read_b128 v[22:25], v233 offset:2048
	s_waitcnt lgkmcnt(0)
	v_mfma_f32_16x16x32_bf16 v[138:141], v[22:25], v[2:5], v[26:29]
	s_nop 2
	ds_read_b128 v[26:29], v233 offset:12288
	v_mfma_f32_16x16x32_bf16 v[142:145], v[22:25], v[6:9], v[30:33]
	v_mfma_f32_16x16x32_bf16 v[130:133], v[22:25], v[10:13], v[34:37]
	v_mfma_f32_16x16x32_bf16 v[134:137], v[22:25], v[14:17], v[38:41]
	ds_read_b128 v[22:25], v233 offset:4096
	s_waitcnt lgkmcnt(0)
	v_mfma_f32_16x16x32_bf16 v[122:125], v[22:25], v[2:5], v[42:45]
	v_mfma_f32_16x16x32_bf16 v[126:129], v[22:25], v[6:9], v[46:49]
	v_mfma_f32_16x16x32_bf16 v[114:117], v[22:25], v[10:13], v[50:53]
	v_mfma_f32_16x16x32_bf16 v[118:121], v[22:25], v[14:17], v[54:57]
	ds_read_b128 v[22:25], v233 offset:6144
	s_waitcnt lgkmcnt(0)
	v_mfma_f32_16x16x32_bf16 v[78:81], v[22:25], v[2:5], v[58:61]
	v_mfma_f32_16x16x32_bf16 v[82:85], v[22:25], v[6:9], v[62:65]
	v_mfma_f32_16x16x32_bf16 v[70:73], v[22:25], v[10:13], v[66:69]
	v_mfma_f32_16x16x32_bf16 v[74:77], v[22:25], v[14:17], v[162:165]
	ds_read_b128 v[22:25], v233 offset:8192
	s_nop 1
	ds_read_b128 v[162:165], v233 offset:14336
	s_waitcnt lgkmcnt(1)
	v_mfma_f32_16x16x32_bf16 v[62:65], v[22:25], v[2:5], v[182:185]
	v_mfma_f32_16x16x32_bf16 v[66:69], v[22:25], v[6:9], v[186:189]
	v_mfma_f32_16x16x32_bf16 v[54:57], v[22:25], v[10:13], v[190:193]
	v_mfma_f32_16x16x32_bf16 v[58:61], v[22:25], v[14:17], v[212:215]
	ds_read_b128 v[22:25], v233 offset:10240
	s_waitcnt lgkmcnt(0)
	v_mfma_f32_16x16x32_bf16 v[46:49], v[22:25], v[2:5], v[216:219]
	v_mfma_f32_16x16x32_bf16 v[50:53], v[22:25], v[6:9], v[220:223]
	v_mfma_f32_16x16x32_bf16 v[38:41], v[22:25], v[10:13], v[234:237]
	v_mfma_f32_16x16x32_bf16 v[42:45], v[22:25], v[14:17], v[238:241]
	v_mfma_f32_16x16x32_bf16 v[30:33], v[26:29], v[2:5], v[242:245]
	v_mfma_f32_16x16x32_bf16 v[34:37], v[26:29], v[6:9], v[246:249]
	v_mfma_f32_16x16x32_bf16 v[22:25], v[26:29], v[10:13], v[250:253]
	v_mfma_f32_16x16x32_bf16 v[26:29], v[26:29], v[14:17], v[208:211]
	v_mfma_f32_16x16x32_bf16 v[166:169], v[162:165], v[2:5], v[166:169]
	v_mfma_f32_16x16x32_bf16 v[170:173], v[162:165], v[6:9], v[170:173]
	v_mfma_f32_16x16x32_bf16 v[2:5], v[162:165], v[10:13], v[174:177]
	v_mfma_f32_16x16x32_bf16 v[6:9], v[162:165], v[14:17], v[178:181]
	v_mov_b32_e32 v14, v195
	s_barrier
; DI int tidx() { int t = threadIdx.x; asm volatile("" : "+v"(t)); return t; }
; template <int EPI>
; DI void gemm_phase(const P& p, int l, const u16* __restrict__ A, const u16* __restrict__ Bt, int mpx, char* lds) {
;     ...
;   __syncthreads();
;   GSTORE(As0, Bs0)
;   const int tid_e = tidx();
;   const int lane = tid_e & 63, w = tid_e >> 6, r = lane & 15, g = lane >> 4, wm = w >> 2, wn = w & 3;
;   if constexpr (EPI == 1) {
;     const float alpha = 1.4142135623730951f;
;     float* Cw = (float*)(lds + 65536) + w * (16 * 68);
;     const int mr = m0 < MLAT ? (m0 >> 11) : 16;
;     const int colw = n0 + wn * 64;
;     const float* gate = p.mod + (size_t)(l * 17 + mr) * 3072 + 2048 + colw;
;     const float* xr = ((l == 0) ? (m0 < MLAT ? p.x + (size_t)m0 * 1024 : p.ctx + (size_t)(m0 - MLAT) * 1024)
;                                 : p.out + (size_t)m0 * 1024) + (size_t)(wm * 128) * 1024 + colw;
;     float* Z = (float*)p.slab + (size_t)(m0 + wm * 128) * 1024 + colw;
;     const int c4 = (lane & 15) * 4, rr0 = lane >> 4;
;     const float4 gt = *(const float4*)(gate + c4);
;     float4 xn[4];
; #pragma unroll
;     for (int i = 0; i < 4; ++i) xn[i] = *(const float4*)(xr + (size_t)(rr0 + 4 * i) * 1024 + c4);
; #pragma unroll
;     for (int mi = 0; mi < 8; ++mi) {
;       float4 xv[4];
; #pragma unroll
;       for (int i = 0; i < 4; ++i) xv[i] = xn[i];
;       if (mi < 7) {
; #pragma unroll
;         for (int i = 0; i < 4; ++i) xn[i] = *(const float4*)(xr + (size_t)((mi + 1) * 16 + rr0 + 4 * i) * 1024 + c4);
;       }
; #pragma unroll
;       for (int ni = 0; ni < 4; ++ni)
; #pragma unroll
;         for (int j = 0; j < 4; ++j) Cw[(g * 4 + j) * 68 + ni * 16 + r] = acc[mi][ni][j];
;       __builtin_amdgcn_fence(__ATOMIC_RELEASE, "wavefront");
; #pragma unroll
;       for (int i = 0; i < 4; ++i) {
;         const int row = rr0 + 4 * i;
;         const float4 a = *(const float4*)&Cw[row * 68 + c4];
;         float4 z;
;         z.x = alpha * xv[i].x + gt.x * a.x;
;         z.y = alpha * xv[i].y + gt.y * a.y;
;         z.z = alpha * xv[i].z + gt.z * a.z;
;         z.w = alpha * xv[i].w + gt.w * a.w;
;         *(float4*)(Z + (size_t)(mi * 16 + row) * 1024 + c4) = z;
	s_waitcnt vmcnt(7)
	ds_write_b128 v198, v[18:21]
	s_waitcnt vmcnt(5)
	ds_write_b128 v198, v[86:89] offset:8192
	s_waitcnt vmcnt(4)
	ds_write_b128 v198, v[90:93] offset:16384
	s_waitcnt vmcnt(3)
	ds_write_b128 v198, v[94:97] offset:24576
	ds_write_b128 v198, v[98:101] offset:32768
	s_waitcnt vmcnt(2)
	ds_write_b128 v198, v[102:105] offset:40960
	s_waitcnt vmcnt(1)
	ds_write_b128 v198, v[106:109] offset:49152
	s_waitcnt vmcnt(0)
	ds_write_b128 v198, v[110:113] offset:57344
	v_readfirstlane_b32 s62, v195
	s_lshr_b32 s62, s62, 6
	s_and_b32 s63, s62, 3
	s_lshr_b32 s68, s62, 2
	s_lshl_b32 s63, s63, 6
	s_add_i32 s63, s63, s61
	s_lshl_b32 s68, s68, 7
	s_add_i32 s68, s68, s60
	s_min_u32 s2, s60, 0x8000
	s_lshr_b32 s2, s2, 11
	s_mul_i32 s69, s50, 17
	s_add_i32 s2, s2, s69
	s_mul_i32 s2, s2, 0x3000
	s_lshl_b32 s69, s63, 2
	s_add_i32 s2, s2, s69
	s_addk_i32 s2, 0x2000
	v_readlane_b32 s70, v255, 30
	v_readlane_b32 s71, v255, 31
	s_add_u32 s70, s70, s2
	s_addc_u32 s71, s71, 0
	v_and_b32_e32 v251, 15, v226
	v_lshrrev_b32_e32 v252, 4, v226
	v_lshlrev_b32_e32 v253, 4, v251
	global_load_dwordx4 v[244:247], v253, s[70:71]
	v_lshl_add_u32 v250, v252, 12, v253
	s_cmp_lt_u32 s60, 0x8000
	s_cselect_b32 s2, 0, 16
	s_cselect_b32 s69, 0, 0x8000
	s_cmp_eq_u32 s50, 0
	s_cselect_b32 s2, s2, 0x88
	s_cselect_b32 s69, s69, 0
	s_add_u32 s70, s96, s2
	s_addc_u32 s71, s97, 0
	s_load_dwordx2 s[64:65], s[70:71], 0x0
	s_sub_i32 s69, s68, s69
	s_mov_b32 s70, s69
	s_mov_b32 s71, 0
	s_lshl_b64 s[70:71], s[70:71], 12
	s_lshl_b32 s2, s63, 2
	s_add_u32 s70, s70, s2
	s_addc_u32 s71, s71, 0
	s_waitcnt lgkmcnt(0)
	s_add_u32 s64, s64, s70
	s_addc_u32 s65, s65, s71
	s_mov_b32 s70, s68
	s_mov_b32 s71, 0
	s_lshl_b64 s[70:71], s[70:71], 12
	s_add_u32 s70, s70, s2
	s_addc_u32 s71, s71, 0
	s_add_u32 s66, s18, s70
	s_addc_u32 s67, s19, s71
	s_mul_i32 s2, s62, 0x1100
	s_add_i32 s2, s2, s78
	v_mul_u32_u24_e32 v248, 0x440, v252
	v_lshl_add_u32 v248, v251, 2, v248
	v_add_u32_e32 v248, s2, v248
	v_mul_u32_u24_e32 v249, 0x110, v252
	v_add_u32_e32 v249, v249, v253
	v_add_u32_e32 v249, s2, v249
	global_load_dwordx4 v[86:89], v250, s[64:65]
	s_add_u32 s64, s64, 0x4000
	s_addc_u32 s65, s65, 0
	global_load_dwordx4 v[90:93], v250, s[64:65]
	s_add_u32 s64, s64, 0x4000
	s_addc_u32 s65, s65, 0
	global_load_dwordx4 v[94:97], v250, s[64:65]
	s_add_u32 s64, s64, 0x4000
	s_addc_u32 s65, s65, 0
	global_load_dwordx4 v[98:101], v250, s[64:65]
	s_add_u32 s64, s64, 0x4000
	s_addc_u32 s65, s65, 0
	global_load_dwordx4 v[102:105], v250, s[64:65]
	s_add_u32 s64, s64, 0x4000
	s_addc_u32 s65, s65, 0
	global_load_dwordx4 v[106:109], v250, s[64:65]
	s_add_u32 s64, s64, 0x4000
	s_addc_u32 s65, s65, 0
	global_load_dwordx4 v[110:113], v250, s[64:65]
	s_add_u32 s64, s64, 0x4000
	s_addc_u32 s65, s65, 0
	global_load_dwordx4 v[174:177], v250, s[64:65]
	s_add_u32 s64, s64, 0x4000
	s_addc_u32 s65, s65, 0
	global_load_dwordx4 v[178:181], v250, s[64:65]
	s_add_u32 s64, s64, 0x4000
	s_addc_u32 s65, s65, 0
	global_load_dwordx4 v[182:185], v250, s[64:65]
	s_add_u32 s64, s64, 0x4000
	s_addc_u32 s65, s65, 0
	global_load_dwordx4 v[186:189], v250, s[64:65]
	s_add_u32 s64, s64, 0x4000
	s_addc_u32 s65, s65, 0
	global_load_dwordx4 v[190:193], v250, s[64:65]
	s_add_u32 s64, s64, 0x4000
	s_addc_u32 s65, s65, 0
	global_load_dwordx4 v[212:215], v250, s[64:65]
	s_add_u32 s64, s64, 0x4000
	s_addc_u32 s65, s65, 0
	global_load_dwordx4 v[216:219], v250, s[64:65]
	s_add_u32 s64, s64, 0x4000
	s_addc_u32 s65, s65, 0
	global_load_dwordx4 v[220:223], v250, s[64:65]
	s_add_u32 s64, s64, 0x4000
	s_addc_u32 s65, s65, 0
	global_load_dwordx4 v[240:243], v250, s[64:65]
	s_add_u32 s64, s64, 0x4000
	s_addc_u32 s65, s65, 0
	ds_write2_b32 v248, v146, v154 offset0:0 offset1:16
	ds_write2_b32 v248, v150, v158 offset0:32 offset1:48
	ds_write2_b32 v248, v147, v155 offset0:68 offset1:84
	ds_write2_b32 v248, v151, v159 offset0:100 offset1:116
	ds_write2_b32 v248, v148, v156 offset0:136 offset1:152
	ds_write2_b32 v248, v152, v160 offset0:168 offset1:184
	ds_write2_b32 v248, v149, v157 offset0:204 offset1:220
	ds_write2_b32 v248, v153, v161 offset0:236 offset1:252
	ds_read_b128 v[10:13], v249 offset:0
	ds_read_b128 v[14:17], v249 offset:1088
	ds_read_b128 v[18:21], v249 offset:2176
	ds_read_b128 v[162:165], v249 offset:3264
	s_waitcnt vmcnt(12)
	s_waitcnt lgkmcnt(3)
	v_mul_f32_e32 v10, v244, v10
	v_mul_f32_e32 v11, v245, v11
	v_mul_f32_e32 v12, v246, v12
	v_mul_f32_e32 v13, v247, v13
	v_fma_f32 v86, v86, s34, v10
	v_fma_f32 v87, v87, s34, v11
	v_fma_f32 v88, v88, s34, v12
	v_fma_f32 v89, v89, s34, v13
	s_waitcnt lgkmcnt(2)
	v_mul_f32_e32 v14, v244, v14
	v_mul_f32_e32 v15, v245, v15
	v_mul_f32_e32 v16, v246, v16
	v_mul_f32_e32 v17, v247, v17
	v_fma_f32 v90, v90, s34, v14
	v_fma_f32 v91, v91, s34, v15
	v_fma_f32 v92, v92, s34, v16
	v_fma_f32 v93, v93, s34, v17
	s_waitcnt lgkmcnt(1)
	v_mul_f32_e32 v18, v244, v18
	v_mul_f32_e32 v19, v245, v19
	v_mul_f32_e32 v20, v246, v20
	v_mul_f32_e32 v21, v247, v21
	v_fma_f32 v94, v94, s34, v18
	v_fma_f32 v95, v95, s34, v19
	v_fma_f32 v96, v96, s34, v20
	v_fma_f32 v97, v97, s34, v21
	s_waitcnt lgkmcnt(0)
	v_mul_f32_e32 v162, v244, v162
	v_mul_f32_e32 v163, v245, v163
	v_mul_f32_e32 v164, v246, v164
	v_mul_f32_e32 v165, v247, v165
	v_fma_f32 v98, v98, s34, v162
	v_fma_f32 v99, v99, s34, v163
	v_fma_f32 v100, v100, s34, v164
	v_fma_f32 v101, v101, s34, v165
	ds_write2_b32 v248, v138, v142 offset0:0 offset1:16
	ds_write2_b32 v248, v130, v134 offset0:32 offset1:48
	ds_write2_b32 v248, v139, v143 offset0:68 offset1:84
	ds_write2_b32 v248, v131, v135 offset0:100 offset1:116
	ds_write2_b32 v248, v140, v144 offset0:136 offset1:152
	ds_write2_b32 v248, v132, v136 offset0:168 offset1:184
	ds_write2_b32 v248, v141, v145 offset0:204 offset1:220
	ds_write2_b32 v248, v133, v137 offset0:236 offset1:252
	ds_read_b128 v[10:13], v249 offset:0
	ds_read_b128 v[14:17], v249 offset:1088
	ds_read_b128 v[18:21], v249 offset:2176
	ds_read_b128 v[162:165], v249 offset:3264
	s_waitcnt vmcnt(8)
; template <int EPI>
; DI void gemm_phase(const P& p, int l, const u16* __restrict__ A, const u16* __restrict__ Bt, int mpx, char* lds) {
;     ...
;       for (int ni = 0; ni < 4; ++ni)
; #pragma unroll
;         for (int j = 0; j < 4; ++j) Cw[(g * 4 + j) * 68 + ni * 16 + r] = acc[mi][ni][j];
;       __builtin_amdgcn_fence(__ATOMIC_RELEASE, "wavefront");
; #pragma unroll
;       for (int i = 0; i < 4; ++i) {
;         const int row = rr0 + 4 * i;
;         const float4 a = *(const float4*)&Cw[row * 68 + c4];
;         float4 z;
;         z.x = alpha * xv[i].x + gt.x * a.x;
;         z.y = alpha * xv[i].y + gt.y * a.y;
;         z.z = alpha * xv[i].z + gt.z * a.z;
;         z.w = alpha * xv[i].w + gt.w * a.w;
;         *(float4*)(Z + (size_t)(mi * 16 + row) * 1024 + c4) = z;
	s_waitcnt lgkmcnt(3)
	v_mul_f32_e32 v10, v244, v10
	v_mul_f32_e32 v11, v245, v11
	v_mul_f32_e32 v12, v246, v12
	v_mul_f32_e32 v13, v247, v13
	v_fma_f32 v102, v102, s34, v10
	v_fma_f32 v103, v103, s34, v11
	v_fma_f32 v104, v104, s34, v12
	v_fma_f32 v105, v105, s34, v13
	s_waitcnt lgkmcnt(2)
	v_mul_f32_e32 v14, v244, v14
	v_mul_f32_e32 v15, v245, v15
	v_mul_f32_e32 v16, v246, v16
	v_mul_f32_e32 v17, v247, v17
	v_fma_f32 v106, v106, s34, v14
	v_fma_f32 v107, v107, s34, v15
	v_fma_f32 v108, v108, s34, v16
	v_fma_f32 v109, v109, s34, v17
	s_waitcnt lgkmcnt(1)
	v_mul_f32_e32 v18, v244, v18
	v_mul_f32_e32 v19, v245, v19
	v_mul_f32_e32 v20, v246, v20
	v_mul_f32_e32 v21, v247, v21
	v_fma_f32 v110, v110, s34, v18
	v_fma_f32 v111, v111, s34, v19
	v_fma_f32 v112, v112, s34, v20
	v_fma_f32 v113, v113, s34, v21
	s_waitcnt lgkmcnt(0)
	v_mul_f32_e32 v162, v244, v162
	v_mul_f32_e32 v163, v245, v163
	v_mul_f32_e32 v164, v246, v164
	v_mul_f32_e32 v165, v247, v165
	v_fma_f32 v174, v174, s34, v162
	v_fma_f32 v175, v175, s34, v163
	v_fma_f32 v176, v176, s34, v164
	v_fma_f32 v177, v177, s34, v165
	ds_write2_b32 v248, v122, v126 offset0:0 offset1:16
	ds_write2_b32 v248, v114, v118 offset0:32 offset1:48
	ds_write2_b32 v248, v123, v127 offset0:68 offset1:84
	ds_write2_b32 v248, v115, v119 offset0:100 offset1:116
	ds_write2_b32 v248, v124, v128 offset0:136 offset1:152
	ds_write2_b32 v248, v116, v120 offset0:168 offset1:184
	ds_write2_b32 v248, v125, v129 offset0:204 offset1:220
	ds_write2_b32 v248, v117, v121 offset0:236 offset1:252
	ds_read_b128 v[10:13], v249 offset:0
	ds_read_b128 v[14:17], v249 offset:1088
	ds_read_b128 v[18:21], v249 offset:2176
	ds_read_b128 v[162:165], v249 offset:3264
	s_waitcnt vmcnt(4)
	s_waitcnt lgkmcnt(3)
	v_mul_f32_e32 v10, v244, v10
	v_mul_f32_e32 v11, v245, v11
	v_mul_f32_e32 v12, v246, v12
	v_mul_f32_e32 v13, v247, v13
	v_fma_f32 v178, v178, s34, v10
	v_fma_f32 v179, v179, s34, v11
	v_fma_f32 v180, v180, s34, v12
	v_fma_f32 v181, v181, s34, v13
	s_waitcnt lgkmcnt(2)
	v_mul_f32_e32 v14, v244, v14
	v_mul_f32_e32 v15, v245, v15
	v_mul_f32_e32 v16, v246, v16
	v_mul_f32_e32 v17, v247, v17
	v_fma_f32 v182, v182, s34, v14
	v_fma_f32 v183, v183, s34, v15
	v_fma_f32 v184, v184, s34, v16
	v_fma_f32 v185, v185, s34, v17
	s_waitcnt lgkmcnt(1)
	v_mul_f32_e32 v18, v244, v18
	v_mul_f32_e32 v19, v245, v19
	v_mul_f32_e32 v20, v246, v20
	v_mul_f32_e32 v21, v247, v21
	v_fma_f32 v186, v186, s34, v18
	v_fma_f32 v187, v187, s34, v19
	v_fma_f32 v188, v188, s34, v20
	v_fma_f32 v189, v189, s34, v21
	s_waitcnt lgkmcnt(0)
	v_mul_f32_e32 v162, v244, v162
	v_mul_f32_e32 v163, v245, v163
	v_mul_f32_e32 v164, v246, v164
	v_mul_f32_e32 v165, v247, v165
	v_fma_f32 v190, v190, s34, v162
	v_fma_f32 v191, v191, s34, v163
	v_fma_f32 v192, v192, s34, v164
	v_fma_f32 v193, v193, s34, v165
	ds_write2_b32 v248, v78, v82 offset0:0 offset1:16
	ds_write2_b32 v248, v70, v74 offset0:32 offset1:48
	ds_write2_b32 v248, v79, v83 offset0:68 offset1:84
	ds_write2_b32 v248, v71, v75 offset0:100 offset1:116
	ds_write2_b32 v248, v80, v84 offset0:136 offset1:152
	ds_write2_b32 v248, v72, v76 offset0:168 offset1:184
	ds_write2_b32 v248, v81, v85 offset0:204 offset1:220
	ds_write2_b32 v248, v73, v77 offset0:236 offset1:252
	ds_read_b128 v[10:13], v249 offset:0
	ds_read_b128 v[14:17], v249 offset:1088
	ds_read_b128 v[18:21], v249 offset:2176
	ds_read_b128 v[162:165], v249 offset:3264
	s_waitcnt vmcnt(0)
	s_waitcnt lgkmcnt(3)
	v_mul_f32_e32 v10, v244, v10
	v_mul_f32_e32 v11, v245, v11
	v_mul_f32_e32 v12, v246, v12
	v_mul_f32_e32 v13, v247, v13
	v_fma_f32 v212, v212, s34, v10
	v_fma_f32 v213, v213, s34, v11
	v_fma_f32 v214, v214, s34, v12
	v_fma_f32 v215, v215, s34, v13
	s_waitcnt lgkmcnt(2)
	v_mul_f32_e32 v14, v244, v14
	v_mul_f32_e32 v15, v245, v15
	v_mul_f32_e32 v16, v246, v16
	v_mul_f32_e32 v17, v247, v17
	v_fma_f32 v216, v216, s34, v14
	v_fma_f32 v217, v217, s34, v15
	v_fma_f32 v218, v218, s34, v16
	v_fma_f32 v219, v219, s34, v17
	s_waitcnt lgkmcnt(1)
	v_mul_f32_e32 v18, v244, v18
	v_mul_f32_e32 v19, v245, v19
	v_mul_f32_e32 v20, v246, v20
	v_mul_f32_e32 v21, v247, v21
	v_fma_f32 v220, v220, s34, v18
	v_fma_f32 v221, v221, s34, v19
	v_fma_f32 v222, v222, s34, v20
	v_fma_f32 v223, v223, s34, v21
	s_waitcnt lgkmcnt(0)
; template <int EPI>
; DI void gemm_phase(const P& p, int l, const u16* __restrict__ A, const u16* __restrict__ Bt, int mpx, char* lds) {
;     ...
;     for (int mi = 0; mi < 8; ++mi) {
;       float4 xv[4];
; #pragma unroll
;       for (int i = 0; i < 4; ++i) xv[i] = xn[i];
;       if (mi < 7) {
; #pragma unroll
;         for (int i = 0; i < 4; ++i) xn[i] = *(const float4*)(xr + (size_t)((mi + 1) * 16 + rr0 + 4 * i) * 1024 + c4);
;       }
; #pragma unroll
;       for (int ni = 0; ni < 4; ++ni)
; #pragma unroll
;         for (int j = 0; j < 4; ++j) Cw[(g * 4 + j) * 68 + ni * 16 + r] = acc[mi][ni][j];
;       __builtin_amdgcn_fence(__ATOMIC_RELEASE, "wavefront");
; #pragma unroll
;       for (int i = 0; i < 4; ++i) {
;         const int row = rr0 + 4 * i;
;         const float4 a = *(const float4*)&Cw[row * 68 + c4];
;         float4 z;
;         z.x = alpha * xv[i].x + gt.x * a.x;
;         z.y = alpha * xv[i].y + gt.y * a.y;
;         z.z = alpha * xv[i].z + gt.z * a.z;
;         z.w = alpha * xv[i].w + gt.w * a.w;
;         *(float4*)(Z + (size_t)(mi * 16 + row) * 1024 + c4) = z;
	v_mul_f32_e32 v162, v244, v162
	v_mul_f32_e32 v163, v245, v163
	v_mul_f32_e32 v164, v246, v164
	v_mul_f32_e32 v165, v247, v165
	v_fma_f32 v240, v240, s34, v162
	v_fma_f32 v241, v241, s34, v163
	v_fma_f32 v242, v242, s34, v164
	v_fma_f32 v243, v243, s34, v165
	global_load_dwordx4 v[146:149], v250, s[64:65]
	s_add_u32 s64, s64, 0x4000
	s_addc_u32 s65, s65, 0
	global_load_dwordx4 v[154:157], v250, s[64:65]
	s_add_u32 s64, s64, 0x4000
	s_addc_u32 s65, s65, 0
	global_load_dwordx4 v[150:153], v250, s[64:65]
	s_add_u32 s64, s64, 0x4000
	s_addc_u32 s65, s65, 0
	global_load_dwordx4 v[158:161], v250, s[64:65]
	s_add_u32 s64, s64, 0x4000
	s_addc_u32 s65, s65, 0
	global_load_dwordx4 v[138:141], v250, s[64:65]
	s_add_u32 s64, s64, 0x4000
	s_addc_u32 s65, s65, 0
	global_load_dwordx4 v[142:145], v250, s[64:65]
	s_add_u32 s64, s64, 0x4000
	s_addc_u32 s65, s65, 0
	global_load_dwordx4 v[130:133], v250, s[64:65]
	s_add_u32 s64, s64, 0x4000
	s_addc_u32 s65, s65, 0
	global_load_dwordx4 v[134:137], v250, s[64:65]
	s_add_u32 s64, s64, 0x4000
	s_addc_u32 s65, s65, 0
	global_load_dwordx4 v[122:125], v250, s[64:65]
	s_add_u32 s64, s64, 0x4000
	s_addc_u32 s65, s65, 0
	global_load_dwordx4 v[126:129], v250, s[64:65]
	s_add_u32 s64, s64, 0x4000
	s_addc_u32 s65, s65, 0
	global_load_dwordx4 v[114:117], v250, s[64:65]
	s_add_u32 s64, s64, 0x4000
	s_addc_u32 s65, s65, 0
	global_load_dwordx4 v[118:121], v250, s[64:65]
	s_add_u32 s64, s64, 0x4000
	s_addc_u32 s65, s65, 0
	global_load_dwordx4 v[78:81], v250, s[64:65]
	s_add_u32 s64, s64, 0x4000
	s_addc_u32 s65, s65, 0
	global_load_dwordx4 v[82:85], v250, s[64:65]
	s_add_u32 s64, s64, 0x4000
	s_addc_u32 s65, s65, 0
	global_load_dwordx4 v[70:73], v250, s[64:65]
	s_add_u32 s64, s64, 0x4000
	s_addc_u32 s65, s65, 0
	global_load_dwordx4 v[74:77], v250, s[64:65]
	s_add_u32 s64, s64, 0x4000
	s_addc_u32 s65, s65, 0
	global_store_dwordx4 v250, v[86:89], s[66:67]
	s_add_u32 s66, s66, 0x4000
	s_addc_u32 s67, s67, 0
	global_store_dwordx4 v250, v[90:93], s[66:67]
	s_add_u32 s66, s66, 0x4000
	s_addc_u32 s67, s67, 0
	global_store_dwordx4 v250, v[94:97], s[66:67]
	s_add_u32 s66, s66, 0x4000
	s_addc_u32 s67, s67, 0
	global_store_dwordx4 v250, v[98:101], s[66:67]
	s_add_u32 s66, s66, 0x4000
	s_addc_u32 s67, s67, 0
	global_store_dwordx4 v250, v[102:105], s[66:67]
	s_add_u32 s66, s66, 0x4000
	s_addc_u32 s67, s67, 0
	global_store_dwordx4 v250, v[106:109], s[66:67]
	s_add_u32 s66, s66, 0x4000
	s_addc_u32 s67, s67, 0
	global_store_dwordx4 v250, v[110:113], s[66:67]
	s_add_u32 s66, s66, 0x4000
	s_addc_u32 s67, s67, 0
	global_store_dwordx4 v250, v[174:177], s[66:67]
	s_add_u32 s66, s66, 0x4000
	s_addc_u32 s67, s67, 0
	global_store_dwordx4 v250, v[178:181], s[66:67]
	s_add_u32 s66, s66, 0x4000
	s_addc_u32 s67, s67, 0
	global_store_dwordx4 v250, v[182:185], s[66:67]
	s_add_u32 s66, s66, 0x4000
	s_addc_u32 s67, s67, 0
	global_store_dwordx4 v250, v[186:189], s[66:67]
	s_add_u32 s66, s66, 0x4000
	s_addc_u32 s67, s67, 0
	global_store_dwordx4 v250, v[190:193], s[66:67]
	s_add_u32 s66, s66, 0x4000
	s_addc_u32 s67, s67, 0
	global_store_dwordx4 v250, v[212:215], s[66:67]
	s_add_u32 s66, s66, 0x4000
	s_addc_u32 s67, s67, 0
	global_store_dwordx4 v250, v[216:219], s[66:67]
	s_add_u32 s66, s66, 0x4000
	s_addc_u32 s67, s67, 0
	global_store_dwordx4 v250, v[220:223], s[66:67]
	s_add_u32 s66, s66, 0x4000
	s_addc_u32 s67, s67, 0
	global_store_dwordx4 v250, v[240:243], s[66:67]
	s_add_u32 s66, s66, 0x4000
	s_addc_u32 s67, s67, 0
	ds_write2_b32 v248, v62, v66 offset0:0 offset1:16
	ds_write2_b32 v248, v54, v58 offset0:32 offset1:48
	ds_write2_b32 v248, v63, v67 offset0:68 offset1:84
	ds_write2_b32 v248, v55, v59 offset0:100 offset1:116
	ds_write2_b32 v248, v64, v68 offset0:136 offset1:152
	ds_write2_b32 v248, v56, v60 offset0:168 offset1:184
	ds_write2_b32 v248, v65, v69 offset0:204 offset1:220
	ds_write2_b32 v248, v57, v61 offset0:236 offset1:252
	ds_read_b128 v[10:13], v249 offset:0
	ds_read_b128 v[14:17], v249 offset:1088
	ds_read_b128 v[18:21], v249 offset:2176
	ds_read_b128 v[162:165], v249 offset:3264
	s_waitcnt vmcnt(28)
	s_waitcnt lgkmcnt(3)
	v_mul_f32_e32 v10, v244, v10
	v_mul_f32_e32 v11, v245, v11
	v_mul_f32_e32 v12, v246, v12
	v_mul_f32_e32 v13, v247, v13
	v_fma_f32 v146, v146, s34, v10
	v_fma_f32 v147, v147, s34, v11
	v_fma_f32 v148, v148, s34, v12
	v_fma_f32 v149, v149, s34, v13
	s_waitcnt lgkmcnt(2)
	v_mul_f32_e32 v14, v244, v14
	v_mul_f32_e32 v15, v245, v15
	v_mul_f32_e32 v16, v246, v16
	v_mul_f32_e32 v17, v247, v17
	v_fma_f32 v154, v154, s34, v14
	v_fma_f32 v155, v155, s34, v15
	v_fma_f32 v156, v156, s34, v16
	v_fma_f32 v157, v157, s34, v17
	s_waitcnt lgkmcnt(1)
	v_mul_f32_e32 v18, v244, v18
	v_mul_f32_e32 v19, v245, v19
	v_mul_f32_e32 v20, v246, v20
	v_mul_f32_e32 v21, v247, v21
	v_fma_f32 v150, v150, s34, v18
	v_fma_f32 v151, v151, s34, v19
	v_fma_f32 v152, v152, s34, v20
	v_fma_f32 v153, v153, s34, v21
	s_waitcnt lgkmcnt(0)
	v_mul_f32_e32 v162, v244, v162
	v_mul_f32_e32 v163, v245, v163
	v_mul_f32_e32 v164, v246, v164
	v_mul_f32_e32 v165, v247, v165
	v_fma_f32 v158, v158, s34, v162
	v_fma_f32 v159, v159, s34, v163
	v_fma_f32 v160, v160, s34, v164
	v_fma_f32 v161, v161, s34, v165
	ds_write2_b32 v248, v46, v50 offset0:0 offset1:16
	ds_write2_b32 v248, v38, v42 offset0:32 offset1:48
	ds_write2_b32 v248, v47, v51 offset0:68 offset1:84
	ds_write2_b32 v248, v39, v43 offset0:100 offset1:116
	ds_write2_b32 v248, v48, v52 offset0:136 offset1:152
	ds_write2_b32 v248, v40, v44 offset0:168 offset1:184
	ds_write2_b32 v248, v49, v53 offset0:204 offset1:220
	ds_write2_b32 v248, v41, v45 offset0:236 offset1:252
	ds_read_b128 v[10:13], v249 offset:0
	ds_read_b128 v[14:17], v249 offset:1088
	ds_read_b128 v[18:21], v249 offset:2176
	ds_read_b128 v[162:165], v249 offset:3264
	s_waitcnt vmcnt(24)
; template <int EPI>
; DI void gemm_phase(const P& p, int l, const u16* __restrict__ A, const u16* __restrict__ Bt, int mpx, char* lds) {
;     ...
;     for (int mi = 0; mi < 8; ++mi) {
;       float4 xv[4];
; #pragma unroll
;       for (int i = 0; i < 4; ++i) xv[i] = xn[i];
;       if (mi < 7) {
; #pragma unroll
;         for (int i = 0; i < 4; ++i) xn[i] = *(const float4*)(xr + (size_t)((mi + 1) * 16 + rr0 + 4 * i) * 1024 + c4);
;       }
; #pragma unroll
;       for (int ni = 0; ni < 4; ++ni)
; #pragma unroll
;         for (int j = 0; j < 4; ++j) Cw[(g * 4 + j) * 68 + ni * 16 + r] = acc[mi][ni][j];
;       __builtin_amdgcn_fence(__ATOMIC_RELEASE, "wavefront");
; #pragma unroll
;       for (int i = 0; i < 4; ++i) {
;         const int row = rr0 + 4 * i;
;         const float4 a = *(const float4*)&Cw[row * 68 + c4];
;         float4 z;
;         z.x = alpha * xv[i].x + gt.x * a.x;
;         z.y = alpha * xv[i].y + gt.y * a.y;
;         z.z = alpha * xv[i].z + gt.z * a.z;
;         z.w = alpha * xv[i].w + gt.w * a.w;
;         *(float4*)(Z + (size_t)(mi * 16 + row) * 1024 + c4) = z;
;       }
;       __builtin_amdgcn_fence(__ATOMIC_RELEASE, "wavefront");
;     }
;     ...
;   if (!has_next) break;
;   t = tn; m0 = m1; n0 = n1; Ag = Agn; Bg = Bgn;
	s_waitcnt lgkmcnt(3)
	v_mul_f32_e32 v10, v244, v10
	v_mul_f32_e32 v11, v245, v11
	v_mul_f32_e32 v12, v246, v12
	v_mul_f32_e32 v13, v247, v13
	v_fma_f32 v138, v138, s34, v10
	v_fma_f32 v139, v139, s34, v11
	v_fma_f32 v140, v140, s34, v12
	v_fma_f32 v141, v141, s34, v13
	s_waitcnt lgkmcnt(2)
	v_mul_f32_e32 v14, v244, v14
	v_mul_f32_e32 v15, v245, v15
	v_mul_f32_e32 v16, v246, v16
	v_mul_f32_e32 v17, v247, v17
	v_fma_f32 v142, v142, s34, v14
	v_fma_f32 v143, v143, s34, v15
	v_fma_f32 v144, v144, s34, v16
	v_fma_f32 v145, v145, s34, v17
	s_waitcnt lgkmcnt(1)
	v_mul_f32_e32 v18, v244, v18
	v_mul_f32_e32 v19, v245, v19
	v_mul_f32_e32 v20, v246, v20
	v_mul_f32_e32 v21, v247, v21
	v_fma_f32 v130, v130, s34, v18
	v_fma_f32 v131, v131, s34, v19
	v_fma_f32 v132, v132, s34, v20
	v_fma_f32 v133, v133, s34, v21
	s_waitcnt lgkmcnt(0)
	v_mul_f32_e32 v162, v244, v162
	v_mul_f32_e32 v163, v245, v163
	v_mul_f32_e32 v164, v246, v164
	v_mul_f32_e32 v165, v247, v165
	v_fma_f32 v134, v134, s34, v162
	v_fma_f32 v135, v135, s34, v163
	v_fma_f32 v136, v136, s34, v164
	v_fma_f32 v137, v137, s34, v165
	ds_write2_b32 v248, v30, v34 offset0:0 offset1:16
	ds_write2_b32 v248, v22, v26 offset0:32 offset1:48
	ds_write2_b32 v248, v31, v35 offset0:68 offset1:84
	ds_write2_b32 v248, v23, v27 offset0:100 offset1:116
	ds_write2_b32 v248, v32, v36 offset0:136 offset1:152
	ds_write2_b32 v248, v24, v28 offset0:168 offset1:184
	ds_write2_b32 v248, v33, v37 offset0:204 offset1:220
	ds_write2_b32 v248, v25, v29 offset0:236 offset1:252
	ds_read_b128 v[10:13], v249 offset:0
	ds_read_b128 v[14:17], v249 offset:1088
	ds_read_b128 v[18:21], v249 offset:2176
	ds_read_b128 v[162:165], v249 offset:3264
	s_waitcnt vmcnt(20)
	s_waitcnt lgkmcnt(3)
	v_mul_f32_e32 v10, v244, v10
	v_mul_f32_e32 v11, v245, v11
	v_mul_f32_e32 v12, v246, v12
	v_mul_f32_e32 v13, v247, v13
	v_fma_f32 v122, v122, s34, v10
	v_fma_f32 v123, v123, s34, v11
	v_fma_f32 v124, v124, s34, v12
	v_fma_f32 v125, v125, s34, v13
	s_waitcnt lgkmcnt(2)
	v_mul_f32_e32 v14, v244, v14
	v_mul_f32_e32 v15, v245, v15
	v_mul_f32_e32 v16, v246, v16
	v_mul_f32_e32 v17, v247, v17
	v_fma_f32 v126, v126, s34, v14
	v_fma_f32 v127, v127, s34, v15
	v_fma_f32 v128, v128, s34, v16
	v_fma_f32 v129, v129, s34, v17
	s_waitcnt lgkmcnt(1)
	v_mul_f32_e32 v18, v244, v18
	v_mul_f32_e32 v19, v245, v19
	v_mul_f32_e32 v20, v246, v20
	v_mul_f32_e32 v21, v247, v21
	v_fma_f32 v114, v114, s34, v18
	v_fma_f32 v115, v115, s34, v19
	v_fma_f32 v116, v116, s34, v20
	v_fma_f32 v117, v117, s34, v21
	s_waitcnt lgkmcnt(0)
	v_mul_f32_e32 v162, v244, v162
	v_mul_f32_e32 v163, v245, v163
	v_mul_f32_e32 v164, v246, v164
	v_mul_f32_e32 v165, v247, v165
	v_fma_f32 v118, v118, s34, v162
	v_fma_f32 v119, v119, s34, v163
	v_fma_f32 v120, v120, s34, v164
	v_fma_f32 v121, v121, s34, v165
	ds_write2_b32 v248, v166, v170 offset0:0 offset1:16
	ds_write2_b32 v248, v2, v6 offset0:32 offset1:48
	ds_write2_b32 v248, v167, v171 offset0:68 offset1:84
	ds_write2_b32 v248, v3, v7 offset0:100 offset1:116
	ds_write2_b32 v248, v168, v172 offset0:136 offset1:152
	ds_write2_b32 v248, v4, v8 offset0:168 offset1:184
	ds_write2_b32 v248, v169, v173 offset0:204 offset1:220
	ds_write2_b32 v248, v5, v9 offset0:236 offset1:252
	ds_read_b128 v[10:13], v249 offset:0
	ds_read_b128 v[14:17], v249 offset:1088
	ds_read_b128 v[18:21], v249 offset:2176
	ds_read_b128 v[162:165], v249 offset:3264
	s_waitcnt vmcnt(16)
	s_waitcnt lgkmcnt(3)
	v_mul_f32_e32 v10, v244, v10
	v_mul_f32_e32 v11, v245, v11
	v_mul_f32_e32 v12, v246, v12
	v_mul_f32_e32 v13, v247, v13
	v_fma_f32 v78, v78, s34, v10
	v_fma_f32 v79, v79, s34, v11
	v_fma_f32 v80, v80, s34, v12
	v_fma_f32 v81, v81, s34, v13
	s_waitcnt lgkmcnt(2)
	v_mul_f32_e32 v14, v244, v14
	v_mul_f32_e32 v15, v245, v15
	v_mul_f32_e32 v16, v246, v16
	v_mul_f32_e32 v17, v247, v17
	v_fma_f32 v82, v82, s34, v14
	v_fma_f32 v83, v83, s34, v15
	v_fma_f32 v84, v84, s34, v16
	v_fma_f32 v85, v85, s34, v17
	s_waitcnt lgkmcnt(1)
	v_mul_f32_e32 v18, v244, v18
	v_mul_f32_e32 v19, v245, v19
	v_mul_f32_e32 v20, v246, v20
	v_mul_f32_e32 v21, v247, v21
	v_fma_f32 v70, v70, s34, v18
	v_fma_f32 v71, v71, s34, v19
	v_fma_f32 v72, v72, s34, v20
	v_fma_f32 v73, v73, s34, v21
	s_waitcnt lgkmcnt(0)
	v_mul_f32_e32 v162, v244, v162
	v_mul_f32_e32 v163, v245, v163
	v_mul_f32_e32 v164, v246, v164
	v_mul_f32_e32 v165, v247, v165
	v_fma_f32 v74, v74, s34, v162
	v_fma_f32 v75, v75, s34, v163
	v_fma_f32 v76, v76, s34, v164
	v_fma_f32 v77, v77, s34, v165
	global_store_dwordx4 v250, v[146:149], s[66:67]
	s_add_u32 s66, s66, 0x4000
	s_addc_u32 s67, s67, 0
	global_store_dwordx4 v250, v[154:157], s[66:67]
	s_add_u32 s66, s66, 0x4000
	s_addc_u32 s67, s67, 0
	global_store_dwordx4 v250, v[150:153], s[66:67]
	s_add_u32 s66, s66, 0x4000
	s_addc_u32 s67, s67, 0
	global_store_dwordx4 v250, v[158:161], s[66:67]
	s_add_u32 s66, s66, 0x4000
	s_addc_u32 s67, s67, 0
	global_store_dwordx4 v250, v[138:141], s[66:67]
	s_add_u32 s66, s66, 0x4000
	s_addc_u32 s67, s67, 0
	global_store_dwordx4 v250, v[142:145], s[66:67]
	s_add_u32 s66, s66, 0x4000
	s_addc_u32 s67, s67, 0
	global_store_dwordx4 v250, v[130:133], s[66:67]
	s_add_u32 s66, s66, 0x4000
	s_addc_u32 s67, s67, 0
	global_store_dwordx4 v250, v[134:137], s[66:67]
	s_add_u32 s66, s66, 0x4000
	s_addc_u32 s67, s67, 0
	global_store_dwordx4 v250, v[122:125], s[66:67]
	s_add_u32 s66, s66, 0x4000
	s_addc_u32 s67, s67, 0
	global_store_dwordx4 v250, v[126:129], s[66:67]
	s_add_u32 s66, s66, 0x4000
	s_addc_u32 s67, s67, 0
	global_store_dwordx4 v250, v[114:117], s[66:67]
	s_add_u32 s66, s66, 0x4000
	s_addc_u32 s67, s67, 0
	global_store_dwordx4 v250, v[118:121], s[66:67]
	s_add_u32 s66, s66, 0x4000
	s_addc_u32 s67, s67, 0
	global_store_dwordx4 v250, v[78:81], s[66:67]
	s_add_u32 s66, s66, 0x4000
	s_addc_u32 s67, s67, 0
	global_store_dwordx4 v250, v[82:85], s[66:67]
	s_add_u32 s66, s66, 0x4000
	s_addc_u32 s67, s67, 0
	global_store_dwordx4 v250, v[70:73], s[66:67]
	s_add_u32 s66, s66, 0x4000
	s_addc_u32 s67, s67, 0
	global_store_dwordx4 v250, v[74:77], s[66:67]
	s_add_u32 s66, s66, 0x4000
	s_addc_u32 s67, s67, 0
	v_mov_b32_e32 v236, 0x358637bd
	s_mov_b32 s60, s58
	s_mov_b32 s61, s59
	s_mov_b64 s[48:49], s[42:43]
	s_mov_b64 s[46:47], s[44:45]
	s_and_b64 vcc, exec, s[40:41]
	s_cbranch_vccz .LBB0_69
	s_branch .LBB0_73
